# prologue x->bf16 conversion loop: 8 chunk loads in flight with counted waits instead of 8 serialized round trips per row
# speedup vs baseline: 1.0357x; 1.0017x over previous
; __global__ void __launch_bounds__(512) mega(Params P) {
;     ...
;           for (int row = gw; row < S; row += NGW) {
;               const f32x4* xr = (const f32x4*)(P.x + (size_t)row * DM) + lane;
;               u32x2* o8 = (u32x2*)(Hb + (size_t)row * DM) + lane; float ss = 0.f;
; #pragma unroll
;               for (int j = 0; j < 8; ++j) { const f32x4 v = xr[64 * j]; ss += (v.x * v.x + v.y * v.y) + (v.z * v.z + v.w * v.w);
;                   u32x2 o; o.x = cvt_pk(v.x, v.y); o.y = cvt_pk(v.z, v.w); o8[64 * j] = o; }
;               ss = wave_sum(ss, lane);
;               if (lane == 0) ssq[row] = ss;
;           } }
.LBB0_88:
	v_add_co_u32_e32 v22, vcc, 0xfffff000, v2
	s_nop 1
	v_addc_co_u32_e32 v23, vcc, -1, v3, vcc
	s_waitcnt lgkmcnt(0)
	global_load_dwordx4 v[46:49], v[22:23], off offset:-3072
	global_load_dwordx4 v[50:53], v[22:23], off offset:-2048
	global_load_dwordx4 v[54:57], v[22:23], off offset:-1024
	global_load_dwordx4 v[58:61], v[2:3], off offset:-4096
	global_load_dwordx4 v[62:65], v[2:3], off offset:-3072
	global_load_dwordx4 v[66:69], v[2:3], off offset:-2048
	global_load_dwordx4 v[70:73], v[2:3], off offset:-1024
	global_load_dwordx4 v[74:77], v[2:3], off
	s_waitcnt vmcnt(7)
	v_cvt_pk_bf16_f32 v18, v46, v47
	v_cvt_pk_bf16_f32 v19, v48, v49
	global_store_dwordx2 v[4:5], v[18:19], off offset:-2048
	v_mul_f32_e32 v15, v47, v47
	v_mul_f32_e32 v17, v49, v49
	v_fmac_f32_e32 v15, v46, v46
	v_fmac_f32_e32 v17, v48, v48
	v_add_f32_e32 v14, v15, v17
	s_waitcnt vmcnt(7)
	v_cvt_pk_bf16_f32 v20, v50, v51
	v_cvt_pk_bf16_f32 v21, v52, v53
	global_store_dwordx2 v[4:5], v[20:21], off offset:-1536
	v_mul_f32_e32 v15, v51, v51
	v_mul_f32_e32 v16, v53, v53
	v_fmac_f32_e32 v15, v50, v50
	v_fmac_f32_e32 v16, v52, v52
	v_add_f32_e32 v15, v15, v16
	v_add_f32_e32 v14, v14, v15
	s_waitcnt vmcnt(7)
	v_cvt_pk_bf16_f32 v18, v54, v55
	v_cvt_pk_bf16_f32 v19, v56, v57
	global_store_dwordx2 v[4:5], v[18:19], off offset:-1024
	v_mul_f32_e32 v15, v55, v55
	v_mul_f32_e32 v16, v57, v57
	v_fmac_f32_e32 v15, v54, v54
	v_fmac_f32_e32 v16, v56, v56
	v_add_f32_e32 v15, v15, v16
	v_add_f32_e32 v14, v14, v15
	s_waitcnt vmcnt(7)
	v_cvt_pk_bf16_f32 v20, v58, v59
	v_cvt_pk_bf16_f32 v21, v60, v61
	global_store_dwordx2 v[4:5], v[20:21], off offset:-512
	v_mul_f32_e32 v15, v59, v59
	v_mul_f32_e32 v16, v61, v61
	v_fmac_f32_e32 v15, v58, v58
	v_fmac_f32_e32 v16, v60, v60
	v_add_f32_e32 v15, v15, v16
	v_add_f32_e32 v14, v14, v15
	s_waitcnt vmcnt(7)
	v_cvt_pk_bf16_f32 v18, v62, v63
	v_cvt_pk_bf16_f32 v19, v64, v65
	global_store_dwordx2 v[4:5], v[18:19], off
	v_mul_f32_e32 v15, v63, v63
	v_mul_f32_e32 v16, v65, v65
	v_fmac_f32_e32 v15, v62, v62
	v_fmac_f32_e32 v16, v64, v64
	v_add_f32_e32 v15, v15, v16
	v_add_f32_e32 v14, v14, v15
	s_waitcnt vmcnt(7)
	v_cvt_pk_bf16_f32 v20, v66, v67
	v_cvt_pk_bf16_f32 v21, v68, v69
	global_store_dwordx2 v[4:5], v[20:21], off offset:512
	v_mul_f32_e32 v15, v67, v67
	v_mul_f32_e32 v16, v69, v69
	v_fmac_f32_e32 v15, v66, v66
	v_fmac_f32_e32 v16, v68, v68
	v_add_f32_e32 v15, v15, v16
	v_add_f32_e32 v14, v14, v15
	s_waitcnt vmcnt(7)
	v_cvt_pk_bf16_f32 v18, v70, v71
	v_cvt_pk_bf16_f32 v19, v72, v73
	global_store_dwordx2 v[4:5], v[18:19], off offset:1024
	v_mul_f32_e32 v15, v71, v71
	v_mul_f32_e32 v16, v73, v73
	v_fmac_f32_e32 v15, v70, v70
	v_fmac_f32_e32 v16, v72, v72
	v_add_f32_e32 v15, v15, v16
	v_add_f32_e32 v14, v14, v15
	s_waitcnt vmcnt(7)
	v_cvt_pk_bf16_f32 v20, v74, v75
	v_cvt_pk_bf16_f32 v21, v76, v77
	global_store_dwordx2 v[4:5], v[20:21], off offset:1536
	v_mul_f32_e32 v15, v75, v75
	v_mul_f32_e32 v16, v77, v77
	v_fmac_f32_e32 v15, v74, v74
	v_fmac_f32_e32 v16, v76, v76
	v_add_f32_e32 v15, v15, v16
	v_add_f32_e32 v14, v14, v15
	ds_bpermute_b32 v15, v7, v14
	s_waitcnt lgkmcnt(0)
	v_add_f32_e32 v14, v14, v15
	ds_bpermute_b32 v15, v8, v14
	s_waitcnt lgkmcnt(0)
	v_add_f32_e32 v14, v14, v15
	ds_bpermute_b32 v15, v9, v14
	s_waitcnt lgkmcnt(0)
	v_add_f32_e32 v14, v14, v15
	ds_bpermute_b32 v15, v10, v14
	s_waitcnt lgkmcnt(0)
	v_add_f32_e32 v14, v14, v15
	ds_bpermute_b32 v15, v11, v14
	s_waitcnt lgkmcnt(0)
	v_add_f32_e32 v14, v14, v15
	ds_bpermute_b32 v15, v12, v14
	s_and_saveexec_b64 s[16:17], s[0:1]
	s_cbranch_execz .LBB0_87
	s_waitcnt lgkmcnt(0)
	v_add_f32_e32 v14, v14, v15
	global_store_dword v13, v14, s[8:9]
	s_branch .LBB0_87
